# resid1: ssq load hoisted above the batch wait; wave_sum via DPP reduction instead of six ds_bpermute round trips
# baseline (speedup 1.0000x reference)
; __device__ __forceinline__ int otid() { int t = threadIdx.x; asm volatile("" : "+v"(t)); return t; }
; #define PIN(i) karg_ptr(8 * (i))
; __device__ __forceinline__ void resid_rows(bf16_t* R, const bf16_t* Y, const float* ssqY, const float* g, float* rstd_out, float* outf, bool wf32, int row_lo, int row_hi, int yoff, int gw, int NGW, int lane) {
;     constexpr int RP = 4;
;     f32x4 gv[2][2];
; #pragma unroll
;     for (int j = 0; j < 2; ++j) { gv[j][0] = *(const f32x4*)(g + 8 * lane + 512 * j); gv[j][1] = *(const f32x4*)(g + 8 * lane + 512 * j + 4); }
;     for (int row0 = row_lo + gw; row0 < row_hi; row0 += RP * NGW) {
; __global__ void __launch_bounds__(512, 2) fwd_megakernel(Params P) {
;     ...
;             const int lane = otid() & 63, gw = bx * 8 + (otid() >> 6);
;             resid_rows(XB, OB, ssqO, PIN(I_LNMPOST) + l * DM, rstdB, nullptr, false, 0, MTOK, 0, gw, NGW, lane);
.LBB0_497:
	s_andn2_b64 vcc, exec, s[4:5]
	s_cbranch_vccnz .LBB0_566
	v_mov_b32_e32 v2, v0
	v_mov_b32_e32 v3, v0
	v_readlane_b32 s4, v255, 4
	v_ashrrev_i32_e32 v3, 6, v3
	s_mov_b64 s[6:7], s[0:1]
	v_add_u32_e32 v92, s4, v3
	s_mov_b64 s[4:5], s[0:1]
	s_mov_b64 s[8:9], s[0:1]
	s_mov_b64 s[14:15], s[0:1]
	v_cmp_gt_i32_e32 vcc, s45, v92
	s_and_saveexec_b64 s[12:13], vcc
	v_readlane_b32 s22, v255, 37
	v_readlane_b32 s23, v255, 38
	v_readlane_b32 s23, v255, 45
	s_cbranch_execz .LBB0_512
	s_load_dwordx2 s[14:15], s[14:15], 0x98
	v_readlane_b32 s16, v255, 49
	s_load_dwordx2 s[8:9], s[8:9], 0x20
	v_readlane_b32 s17, v255, 50
	v_and_b32_e32 v18, 63, v2
	s_waitcnt lgkmcnt(0)
	s_add_u32 s14, s14, 0x2d20000
	s_addc_u32 s15, s15, 0
	s_lshl_b32 s48, s16, 10
	s_lshl_b64 s[16:17], s[48:49], 2
	s_add_u32 s8, s8, s16
	v_lshlrev_b32_e32 v14, 5, v18
	s_addc_u32 s9, s9, s17
	global_load_dwordx4 v[2:5], v14, s[8:9] offset:2048
	global_load_dwordx4 v[6:9], v14, s[8:9] offset:2064
	global_load_dwordx4 v[10:13], v14, s[8:9]
	s_nop 0
	global_load_dwordx4 v[14:17], v14, s[8:9] offset:16
	v_and_b32_e32 v19, 64, v246
	v_add_u32_e32 v19, 64, v19
	v_xor_b32_e32 v20, 1, v246
	s_load_dwordx2 s[8:9], s[4:5], 0x98
	s_nop 0
	s_load_dwordx2 s[6:7], s[6:7], 0x98
	v_cmp_lt_i32_e64 s[4:5], v20, v19
	v_lshlrev_b32_e32 v162, 4, v18
	v_cmp_eq_u32_e32 vcc, 63, v18
	v_cndmask_b32_e64 v20, v246, v20, s[4:5]
	v_lshlrev_b32_e32 v96, 2, v20
	v_xor_b32_e32 v20, 2, v246
	v_cmp_lt_i32_e64 s[4:5], v20, v19
	s_mov_b64 s[16:17], 0
	s_nop 0
	v_cndmask_b32_e64 v20, v246, v20, s[4:5]
	v_lshlrev_b32_e32 v97, 2, v20
	v_xor_b32_e32 v20, 4, v246
	v_cmp_lt_i32_e64 s[4:5], v20, v19
	s_nop 1
	v_cndmask_b32_e64 v20, v246, v20, s[4:5]
	v_lshlrev_b32_e32 v98, 2, v20
	v_xor_b32_e32 v20, 8, v246
	v_cmp_lt_i32_e64 s[4:5], v20, v19
	s_nop 1
	v_cndmask_b32_e64 v20, v246, v20, s[4:5]
	v_lshlrev_b32_e32 v99, 2, v20
	v_xor_b32_e32 v20, 16, v246
	v_cmp_lt_i32_e64 s[4:5], v20, v19
	s_nop 1
	v_cndmask_b32_e64 v20, v246, v20, s[4:5]
	v_lshlrev_b32_e32 v100, 2, v20
	v_xor_b32_e32 v20, 32, v246
	v_cmp_lt_i32_e64 s[4:5], v20, v19
	s_nop 1
	v_cndmask_b32_e64 v19, v246, v20, s[4:5]
	v_lshlrev_b32_e32 v101, 2, v19
	s_waitcnt lgkmcnt(0)
	v_lshl_add_u64 v[18:19], s[8:9], 0, v[162:163]
	s_mov_b64 s[4:5], 0x3001000
	v_lshl_add_u64 v[82:83], v[18:19], 0, s[4:5]
	v_lshl_add_u64 v[18:19], s[6:7], 0, v[162:163]
	s_mov_b64 s[4:5], 0x7800000
	v_lshl_add_u64 v[84:85], v[18:19], 0, s[4:5]
	s_branch .LBB0_501

; __device__ __forceinline__ float bflo(unsigned w) { return __uint_as_float(w << 16); }
; __device__ __forceinline__ float bfhi(unsigned w) { return __uint_as_float(w & 0xffff0000u); }
; __device__ __forceinline__ void resid_rows(bf16_t* R, const bf16_t* Y, const float* ssqY, const float* g, float* rstd_out, float* outf, bool wf32, int row_lo, int row_hi, int yoff, int gw, int NGW, int lane) {
;     ...
;     for (int row0 = row_lo + gw; row0 < row_hi; row0 += RP * NGW) {
;         u32x4 rr[RP][2], oo[RP][2]; float ssv[RP];
; #pragma unroll
;         for (int k = 0; k < RP; ++k) { const int row = row0 + k * NGW; const bool ok = row < row_hi; const int rw = ok ? row : row0;
;             ssv[k] = ssqY[rw];
; #pragma unroll
;             for (int j = 0; j < 2; ++j) { const int c = 8 * lane + 512 * j; rr[k][j] = *(const u32x4*)(R + (size_t)rw * DM + c); oo[k][j] = *(const u32x4*)(Y + (size_t)(rw - yoff) * DM + c); } }
; #pragma unroll
;         for (int k = 0; k < RP; ++k) { const int row = row0 + k * NGW; if (row < row_hi) {
;             const float rs = __builtin_amdgcn_rsqf(ssv[k] * (1.0f / DM) + RMS_EPS); float s = 0.f;
; #pragma unroll
;             for (int j = 0; j < 2; ++j) { const int c = 8 * lane + 512 * j; const u32x4 r = rr[k][j], o = oo[k][j]; const f32x4 ga = gv[j][0], gb = gv[j][1];
;                 f32x4 ya, yb; ya[0] = bflo(r.x) + bflo(o.x) * rs * ga[0]; ya[1] = bfhi(r.x) + bfhi(o.x) * rs * ga[1]; ya[2] = bflo(r.y) + bflo(o.y) * rs * ga[2]; ya[3] = bfhi(r.y) + bfhi(o.y) * rs * ga[3];
;                 yb[0] = bflo(r.z) + bflo(o.z) * rs * gb[0]; yb[1] = bfhi(r.z) + bfhi(o.z) * rs * gb[1]; yb[2] = bflo(r.w) + bflo(o.w) * rs * gb[2]; yb[3] = bfhi(r.w) + bfhi(o.w) * rs * gb[3];
;                 if (wf32) { *(f32x4*)(outf + (size_t)row * DM + c) = ya; *(f32x4*)(outf + (size_t)row * DM + c + 4) = yb; }
;                 s += (ya[0] * ya[0] + ya[1] * ya[1]) + (ya[2] * ya[2] + ya[3] * ya[3]) + (yb[0] * yb[0] + yb[1] * yb[1]) + (yb[2] * yb[2] + yb[3] * yb[3]);
;                 u32x4 w; w.x = pk2(ya[0], ya[1]); w.y = pk2(ya[2], ya[3]); w.z = pk2(yb[0], yb[1]); w.w = pk2(yb[2], yb[3]); *(u32x4*)(R + (size_t)row * DM + c) = w; }
;             s = wave_sum(s); if (lane == 0) rstd_out[row] = __builtin_amdgcn_rsqf(s * (1.0f / DM) + RMS_EPS); } }
.LBB0_501:
	v_ashrrev_i32_e32 v93, 31, v92
	v_add_u32_e32 v86, s22, v92
	s_waitcnt lgkmcnt(0)
	v_lshlrev_b64 v[18:19], 11, v[92:93]
	v_cmp_gt_i32_e64 s[8:9], s45, v86
	v_lshl_add_u64 v[94:95], v[82:83], 0, v[18:19]
	v_lshl_add_u64 v[74:75], v[84:85], 0, v[18:19]
	v_cndmask_b32_e64 v18, v92, v86, s[8:9]
	v_ashrrev_i32_e32 v19, 31, v18
	v_lshl_add_u64 v[20:21], v[18:19], 2, s[10:11]
	v_lshlrev_b64 v[18:19], 11, v[18:19]
	v_add_u32_e32 v90, s23, v92
	global_load_dword v87, v[20:21], off
	v_lshl_add_u64 v[20:21], v[82:83], 0, v[18:19]
	v_lshl_add_u64 v[18:19], v[84:85], 0, v[18:19]
	v_cmp_gt_i32_e64 s[6:7], s45, v90
	global_load_dwordx4 v[70:73], v[94:95], off offset:1024
	global_load_dwordx4 v[66:69], v[74:75], off offset:1024
	global_load_dwordx4 v[62:65], v[20:21], off
	global_load_dwordx4 v[58:61], v[18:19], off
	global_load_dwordx4 v[54:57], v[20:21], off offset:1024
	global_load_dwordx4 v[50:53], v[18:19], off offset:1024
	v_cndmask_b32_e64 v18, v92, v90, s[6:7]
	v_ashrrev_i32_e32 v19, 31, v18
	v_lshl_add_u64 v[20:21], v[18:19], 2, s[10:11]
	v_lshlrev_b64 v[18:19], 11, v[18:19]
	v_add_u32_e32 v88, s62, v92
	global_load_dword v91, v[20:21], off
	v_lshl_add_u64 v[20:21], v[82:83], 0, v[18:19]
	v_lshl_add_u64 v[18:19], v[84:85], 0, v[18:19]
	v_cmp_gt_i32_e64 s[4:5], s45, v88
	global_load_dwordx4 v[46:49], v[20:21], off
	global_load_dwordx4 v[42:45], v[18:19], off
	global_load_dwordx4 v[38:41], v[20:21], off offset:1024
	global_load_dwordx4 v[34:37], v[18:19], off offset:1024
	v_cndmask_b32_e64 v18, v92, v88, s[4:5]
	v_ashrrev_i32_e32 v19, 31, v18
	v_lshl_add_u64 v[20:21], v[18:19], 2, s[10:11]
	v_lshlrev_b64 v[18:19], 11, v[18:19]
	global_load_dword v89, v[20:21], off
	v_lshl_add_u64 v[20:21], v[82:83], 0, v[18:19]
	v_lshl_add_u64 v[18:19], v[84:85], 0, v[18:19]
	v_lshl_add_u64 v[102:103], v[92:93], 2, s[10:11]
	global_load_dwordx4 v[30:33], v[20:21], off
	global_load_dwordx4 v[26:29], v[18:19], off
	global_load_dwordx4 v[22:25], v[20:21], off offset:1024
	s_nop 0
	global_load_dwordx4 v[18:21], v[18:19], off offset:1024
	s_nop 0
	global_load_dwordx4 v[74:77], v[74:75], off
	s_nop 0
	global_load_dwordx4 v[78:81], v[94:95], off
	s_nop 0
	global_load_dword v102, v[102:103], off
	s_waitcnt vmcnt(0)
	v_lshlrev_b32_e32 v106, 16, v74
	v_and_b32_e32 v107, 0xffff0000, v74
	v_lshlrev_b32_e32 v104, 16, v78
	v_and_b32_e32 v105, 0xffff0000, v78
	v_lshlrev_b32_e32 v74, 16, v75
	v_and_b32_e32 v75, 0xffff0000, v75
	v_lshlrev_b32_e32 v78, 16, v79
	v_and_b32_e32 v79, 0xffff0000, v79
	s_waitcnt vmcnt(0)
	v_fmamk_f32 v102, v102, 0x3a800000, v244
	v_rsq_f32_e32 v102, v102
	s_nop 0
	v_pk_mul_f32 v[106:107], v[102:103], v[106:107] op_sel_hi:[0,1]
	v_pk_fma_f32 v[104:105], v[10:11], v[106:107], v[104:105]
	v_pk_mul_f32 v[74:75], v[102:103], v[74:75] op_sel_hi:[0,1]
	v_lshlrev_b32_e32 v106, 16, v76
	v_and_b32_e32 v107, 0xffff0000, v76
	v_pk_fma_f32 v[78:79], v[12:13], v[74:75], v[78:79]
	v_lshlrev_b32_e32 v74, 16, v80
	v_and_b32_e32 v75, 0xffff0000, v80
	v_pk_mul_f32 v[106:107], v[102:103], v[106:107] op_sel_hi:[0,1]
	v_lshlrev_b32_e32 v76, 16, v77
	v_and_b32_e32 v77, 0xffff0000, v77
	v_pk_fma_f32 v[106:107], v[14:15], v[106:107], v[74:75]
	v_lshlrev_b32_e32 v74, 16, v81
	v_and_b32_e32 v75, 0xffff0000, v81
	v_pk_mul_f32 v[76:77], v[102:103], v[76:77] op_sel_hi:[0,1]
	v_pk_fma_f32 v[80:81], v[16:17], v[76:77], v[74:75]
	v_cvt_pk_bf16_f32 v74, v104, v105
	v_cvt_pk_bf16_f32 v75, v78, v79
	v_cvt_pk_bf16_f32 v76, v106, v107
	v_cvt_pk_bf16_f32 v77, v80, v81
	global_store_dwordx4 v[94:95], v[74:77], off
	v_pk_mul_f32 v[110:111], v[78:79], v[78:79]
	v_pk_mul_f32 v[114:115], v[80:81], v[80:81]
	v_lshlrev_b32_e32 v76, 16, v66
	v_and_b32_e32 v77, 0xffff0000, v66
	v_lshlrev_b32_e32 v74, 16, v70
	v_and_b32_e32 v75, 0xffff0000, v70
	v_pk_mul_f32 v[76:77], v[102:103], v[76:77] op_sel_hi:[0,1]
	v_lshlrev_b32_e32 v66, 16, v67
	v_and_b32_e32 v67, 0xffff0000, v67
	v_pk_fma_f32 v[74:75], v[2:3], v[76:77], v[74:75]
	v_lshlrev_b32_e32 v70, 16, v71
	v_and_b32_e32 v71, 0xffff0000, v71
	v_pk_mul_f32 v[66:67], v[102:103], v[66:67] op_sel_hi:[0,1]
	v_lshlrev_b32_e32 v76, 16, v68
	v_and_b32_e32 v77, 0xffff0000, v68
	v_pk_fma_f32 v[70:71], v[4:5], v[66:67], v[70:71]
	v_lshlrev_b32_e32 v66, 16, v72
	v_and_b32_e32 v67, 0xffff0000, v72
	v_pk_mul_f32 v[76:77], v[102:103], v[76:77] op_sel_hi:[0,1]
	v_lshlrev_b32_e32 v68, 16, v69
	v_and_b32_e32 v69, 0xffff0000, v69
	v_pk_fma_f32 v[76:77], v[6:7], v[76:77], v[66:67]
	v_lshlrev_b32_e32 v66, 16, v73
	v_and_b32_e32 v67, 0xffff0000, v73
	v_pk_mul_f32 v[68:69], v[102:103], v[68:69] op_sel_hi:[0,1]
	v_pk_fma_f32 v[72:73], v[8:9], v[68:69], v[66:67]
	v_pk_mul_f32 v[66:67], v[74:75], v[74:75]
	v_pk_mul_f32 v[68:69], v[70:71], v[70:71]
	v_pk_mul_f32 v[78:79], v[76:77], v[76:77]
	v_add_f32_e32 v68, v68, v69
	v_add_f32_e32 v66, v66, v67
	v_pk_mul_f32 v[80:81], v[72:73], v[72:73]
	v_add_f32_e32 v66, v66, v68
	v_add_f32_e32 v67, v78, v79
	v_pk_mul_f32 v[108:109], v[104:105], v[104:105]
	v_add_f32_e32 v66, v67, v66
	v_add_f32_e32 v67, v80, v81
	v_pk_mul_f32 v[112:113], v[106:107], v[106:107]
	v_add_f32_e32 v66, v67, v66
	v_add_f32_e32 v67, v110, v111
	v_add_f32_e32 v68, v108, v109
	v_add_f32_e32 v67, v68, v67
	v_add_f32_e32 v68, v112, v113
	v_add_f32_e32 v67, v68, v67
	v_add_f32_e32 v68, v114, v115
	v_add_f32_e32 v67, v68, v67
	v_add_f32_e32 v78, v67, v66
	v_cvt_pk_bf16_f32 v66, v74, v75
	v_cvt_pk_bf16_f32 v67, v70, v71
	v_cvt_pk_bf16_f32 v68, v76, v77
	v_cvt_pk_bf16_f32 v69, v72, v73
	global_store_dwordx4 v[94:95], v[66:69], off offset:1024
	s_nop 1
	v_add_f32_dpp v66, v78, v78 quad_perm:[1,0,3,2] row_mask:0xf bank_mask:0xf
	s_nop 1
	v_add_f32_dpp v66, v66, v66 quad_perm:[2,3,0,1] row_mask:0xf bank_mask:0xf
	s_nop 1
	v_add_f32_dpp v66, v66, v66 row_half_mirror row_mask:0xf bank_mask:0xf
	s_nop 1
	v_add_f32_dpp v66, v66, v66 row_mirror row_mask:0xf bank_mask:0xf
	s_nop 1
	v_add_f32_dpp v66, v66, v66 row_bcast:15 row_mask:0xa bank_mask:0xf
	s_nop 1
	v_add_f32_dpp v66, v66, v66 row_bcast:31 row_mask:0xc bank_mask:0xf
	s_and_saveexec_b64 s[18:19], vcc
	s_cbranch_execz .LBB0_503
	v_fmamk_f32 v66, v66, 0x3a800000, v244
	v_rsq_f32_e32 v68, v66
	v_lshl_add_u64 v[66:67], v[92:93], 2, s[14:15]
	global_store_dword v[66:67], v68, off
; __device__ __forceinline__ float bflo(unsigned w) { return __uint_as_float(w << 16); }
; __device__ __forceinline__ float bfhi(unsigned w) { return __uint_as_float(w & 0xffff0000u); }
; __device__ __forceinline__ void resid_rows(bf16_t* R, const bf16_t* Y, const float* ssqY, const float* g, float* rstd_out, float* outf, bool wf32, int row_lo, int row_hi, int yoff, int gw, int NGW, int lane) {
;     ...
;         for (int k = 0; k < RP; ++k) { const int row = row0 + k * NGW; if (row < row_hi) {
;             const float rs = __builtin_amdgcn_rsqf(ssv[k] * (1.0f / DM) + RMS_EPS); float s = 0.f;
; #pragma unroll
;             for (int j = 0; j < 2; ++j) { const int c = 8 * lane + 512 * j; const u32x4 r = rr[k][j], o = oo[k][j]; const f32x4 ga = gv[j][0], gb = gv[j][1];
;                 f32x4 ya, yb; ya[0] = bflo(r.x) + bflo(o.x) * rs * ga[0]; ya[1] = bfhi(r.x) + bfhi(o.x) * rs * ga[1]; ya[2] = bflo(r.y) + bflo(o.y) * rs * ga[2]; ya[3] = bfhi(r.y) + bfhi(o.y) * rs * ga[3];
;                 yb[0] = bflo(r.z) + bflo(o.z) * rs * gb[0]; yb[1] = bfhi(r.z) + bfhi(o.z) * rs * gb[1]; yb[2] = bflo(r.w) + bflo(o.w) * rs * gb[2]; yb[3] = bfhi(r.w) + bfhi(o.w) * rs * gb[3];
;                 if (wf32) { *(f32x4*)(outf + (size_t)row * DM + c) = ya; *(f32x4*)(outf + (size_t)row * DM + c + 4) = yb; }
;                 s += (ya[0] * ya[0] + ya[1] * ya[1]) + (ya[2] * ya[2] + ya[3] * ya[3]) + (yb[0] * yb[0] + yb[1] * yb[1]) + (yb[2] * yb[2] + yb[3] * yb[3]);
;                 u32x4 w; w.x = pk2(ya[0], ya[1]); w.y = pk2(ya[2], ya[3]); w.z = pk2(yb[0], yb[1]); w.w = pk2(yb[2], yb[3]); *(u32x4*)(R + (size_t)row * DM + c) = w; }
;             s = wave_sum(s); if (lane == 0) rstd_out[row] = __builtin_amdgcn_rsqf(s * (1.0f / DM) + RMS_EPS); } }
.LBB0_503:
	s_or_b64 exec, exec, s[18:19]
	s_and_saveexec_b64 s[18:19], s[8:9]
	s_cbranch_execz .LBB0_506
	v_fmamk_f32 v66, v87, 0x3a800000, v244
	v_rsq_f32_e32 v66, v66
	v_lshlrev_b32_e32 v72, 16, v58
	v_and_b32_e32 v73, 0xffff0000, v58
	v_lshlrev_b32_e32 v70, 16, v62
	v_and_b32_e32 v71, 0xffff0000, v62
	s_waitcnt lgkmcnt(0)
	v_pk_mul_f32 v[72:73], v[66:67], v[72:73] op_sel_hi:[0,1]
	v_lshlrev_b32_e32 v58, 16, v59
	v_and_b32_e32 v59, 0xffff0000, v59
	v_pk_fma_f32 v[70:71], v[10:11], v[72:73], v[70:71]
	v_lshlrev_b32_e32 v62, 16, v63
	v_and_b32_e32 v63, 0xffff0000, v63
	v_pk_mul_f32 v[58:59], v[66:67], v[58:59] op_sel_hi:[0,1]
	v_lshlrev_b32_e32 v72, 16, v60
	v_and_b32_e32 v73, 0xffff0000, v60
	v_pk_fma_f32 v[62:63], v[12:13], v[58:59], v[62:63]
	v_lshlrev_b32_e32 v58, 16, v64
	v_and_b32_e32 v59, 0xffff0000, v64
	v_pk_mul_f32 v[72:73], v[66:67], v[72:73] op_sel_hi:[0,1]
	v_lshlrev_b32_e32 v60, 16, v61
	v_and_b32_e32 v61, 0xffff0000, v61
	v_ashrrev_i32_e32 v87, 31, v86
	v_pk_fma_f32 v[72:73], v[14:15], v[72:73], v[58:59]
	v_lshlrev_b32_e32 v58, 16, v65
	v_and_b32_e32 v59, 0xffff0000, v65
	v_pk_mul_f32 v[60:61], v[66:67], v[60:61] op_sel_hi:[0,1]
	v_lshlrev_b64 v[68:69], 11, v[86:87]
	v_pk_fma_f32 v[64:65], v[16:17], v[60:61], v[58:59]
	v_pk_mul_f32 v[76:77], v[62:63], v[62:63]
	v_cvt_pk_bf16_f32 v58, v70, v71
	v_cvt_pk_bf16_f32 v59, v62, v63
	v_cvt_pk_bf16_f32 v60, v72, v73
	v_cvt_pk_bf16_f32 v61, v64, v65
	v_lshl_add_u64 v[62:63], v[82:83], 0, v[68:69]
	global_store_dwordx4 v[62:63], v[58:61], off
	v_pk_mul_f32 v[74:75], v[70:71], v[70:71]
	v_pk_mul_f32 v[78:79], v[72:73], v[72:73]
	v_lshlrev_b32_e32 v60, 16, v50
	v_and_b32_e32 v61, 0xffff0000, v50
	v_lshlrev_b32_e32 v58, 16, v54
	v_and_b32_e32 v59, 0xffff0000, v54
	v_pk_mul_f32 v[60:61], v[66:67], v[60:61] op_sel_hi:[0,1]
	v_lshlrev_b32_e32 v50, 16, v51
	v_and_b32_e32 v51, 0xffff0000, v51
	v_pk_fma_f32 v[58:59], v[2:3], v[60:61], v[58:59]
	v_lshlrev_b32_e32 v54, 16, v55
	v_and_b32_e32 v55, 0xffff0000, v55
	v_pk_mul_f32 v[50:51], v[66:67], v[50:51] op_sel_hi:[0,1]
	v_lshlrev_b32_e32 v60, 16, v52
	v_and_b32_e32 v61, 0xffff0000, v52
	v_pk_fma_f32 v[54:55], v[4:5], v[50:51], v[54:55]
	v_lshlrev_b32_e32 v50, 16, v56
	v_and_b32_e32 v51, 0xffff0000, v56
	v_pk_mul_f32 v[60:61], v[66:67], v[60:61] op_sel_hi:[0,1]
	v_lshlrev_b32_e32 v52, 16, v53
	v_and_b32_e32 v53, 0xffff0000, v53
	v_pk_fma_f32 v[60:61], v[6:7], v[60:61], v[50:51]
	v_lshlrev_b32_e32 v50, 16, v57
	v_and_b32_e32 v51, 0xffff0000, v57
	v_pk_mul_f32 v[52:53], v[66:67], v[52:53] op_sel_hi:[0,1]
	v_pk_fma_f32 v[56:57], v[8:9], v[52:53], v[50:51]
	v_pk_mul_f32 v[50:51], v[58:59], v[58:59]
	v_pk_mul_f32 v[52:53], v[54:55], v[54:55]
	v_add_f32_e32 v50, v50, v51
	v_add_f32_e32 v52, v52, v53
	v_pk_mul_f32 v[80:81], v[64:65], v[64:65]
	v_pk_mul_f32 v[64:65], v[60:61], v[60:61]
	v_add_f32_e32 v50, v50, v52
	v_add_f32_e32 v52, v76, v77
	v_add_f32_e32 v53, v74, v75
	v_pk_mul_f32 v[66:67], v[56:57], v[56:57]
	v_add_f32_e32 v51, v64, v65
	v_add_f32_e32 v52, v53, v52
	v_add_f32_e32 v53, v78, v79
	v_add_f32_e32 v66, v66, v67
	v_add_f32_e32 v50, v51, v50
	v_add_f32_e32 v51, v80, v81
	v_add_f32_e32 v52, v53, v52
	v_add_f32_e32 v50, v66, v50
	v_add_f32_e32 v51, v51, v52
	v_add_f32_e32 v64, v51, v50
	v_cvt_pk_bf16_f32 v50, v58, v59
	v_cvt_pk_bf16_f32 v51, v54, v55
	v_cvt_pk_bf16_f32 v52, v60, v61
	v_cvt_pk_bf16_f32 v53, v56, v57
	global_store_dwordx4 v[62:63], v[50:53], off offset:1024
	s_nop 1
	v_add_f32_dpp v50, v64, v64 quad_perm:[1,0,3,2] row_mask:0xf bank_mask:0xf
	s_nop 1
	v_add_f32_dpp v50, v50, v50 quad_perm:[2,3,0,1] row_mask:0xf bank_mask:0xf
	s_nop 1
	v_add_f32_dpp v50, v50, v50 row_half_mirror row_mask:0xf bank_mask:0xf
	s_nop 1
	v_add_f32_dpp v50, v50, v50 row_mirror row_mask:0xf bank_mask:0xf
	s_nop 1
	v_add_f32_dpp v50, v50, v50 row_bcast:15 row_mask:0xa bank_mask:0xf
	s_nop 1
	v_add_f32_dpp v50, v50, v50 row_bcast:31 row_mask:0xc bank_mask:0xf
	s_and_b64 exec, exec, vcc
	s_cbranch_execz .LBB0_506
	v_fmamk_f32 v50, v50, 0x3a800000, v244
	v_rsq_f32_e32 v52, v50
	v_lshl_add_u64 v[50:51], v[86:87], 2, s[14:15]
	global_store_dword v[50:51], v52, off
.LBB0_506:
	s_or_b64 exec, exec, s[18:19]
	s_and_saveexec_b64 s[8:9], s[6:7]
	s_cbranch_execz .LBB0_509
	v_fmamk_f32 v50, v91, 0x3a800000, v244
	v_rsq_f32_e32 v50, v50
	v_lshlrev_b32_e32 v56, 16, v42
	v_and_b32_e32 v57, 0xffff0000, v42
	v_lshlrev_b32_e32 v54, 16, v46
	v_and_b32_e32 v55, 0xffff0000, v46
	s_waitcnt lgkmcnt(0)
; __device__ __forceinline__ float bflo(unsigned w) { return __uint_as_float(w << 16); }
; __device__ __forceinline__ float bfhi(unsigned w) { return __uint_as_float(w & 0xffff0000u); }
; __device__ __forceinline__ void resid_rows(bf16_t* R, const bf16_t* Y, const float* ssqY, const float* g, float* rstd_out, float* outf, bool wf32, int row_lo, int row_hi, int yoff, int gw, int NGW, int lane) {
;     ...
;         for (int k = 0; k < RP; ++k) { const int row = row0 + k * NGW; if (row < row_hi) {
;             const float rs = __builtin_amdgcn_rsqf(ssv[k] * (1.0f / DM) + RMS_EPS); float s = 0.f;
; #pragma unroll
;             for (int j = 0; j < 2; ++j) { const int c = 8 * lane + 512 * j; const u32x4 r = rr[k][j], o = oo[k][j]; const f32x4 ga = gv[j][0], gb = gv[j][1];
;                 f32x4 ya, yb; ya[0] = bflo(r.x) + bflo(o.x) * rs * ga[0]; ya[1] = bfhi(r.x) + bfhi(o.x) * rs * ga[1]; ya[2] = bflo(r.y) + bflo(o.y) * rs * ga[2]; ya[3] = bfhi(r.y) + bfhi(o.y) * rs * ga[3];
;                 yb[0] = bflo(r.z) + bflo(o.z) * rs * gb[0]; yb[1] = bfhi(r.z) + bfhi(o.z) * rs * gb[1]; yb[2] = bflo(r.w) + bflo(o.w) * rs * gb[2]; yb[3] = bfhi(r.w) + bfhi(o.w) * rs * gb[3];
;                 if (wf32) { *(f32x4*)(outf + (size_t)row * DM + c) = ya; *(f32x4*)(outf + (size_t)row * DM + c + 4) = yb; }
;                 s += (ya[0] * ya[0] + ya[1] * ya[1]) + (ya[2] * ya[2] + ya[3] * ya[3]) + (yb[0] * yb[0] + yb[1] * yb[1]) + (yb[2] * yb[2] + yb[3] * yb[3]);
;                 u32x4 w; w.x = pk2(ya[0], ya[1]); w.y = pk2(ya[2], ya[3]); w.z = pk2(yb[0], yb[1]); w.w = pk2(yb[2], yb[3]); *(u32x4*)(R + (size_t)row * DM + c) = w; }
;             s = wave_sum(s); if (lane == 0) rstd_out[row] = __builtin_amdgcn_rsqf(s * (1.0f / DM) + RMS_EPS); } }
	v_pk_mul_f32 v[56:57], v[50:51], v[56:57] op_sel_hi:[0,1]
	v_lshlrev_b32_e32 v42, 16, v43
	v_and_b32_e32 v43, 0xffff0000, v43
	v_pk_fma_f32 v[54:55], v[10:11], v[56:57], v[54:55]
	v_lshlrev_b32_e32 v46, 16, v47
	v_and_b32_e32 v47, 0xffff0000, v47
	v_pk_mul_f32 v[42:43], v[50:51], v[42:43] op_sel_hi:[0,1]
	v_lshlrev_b32_e32 v56, 16, v44
	v_and_b32_e32 v57, 0xffff0000, v44
	v_pk_fma_f32 v[46:47], v[12:13], v[42:43], v[46:47]
	v_lshlrev_b32_e32 v42, 16, v48
	v_and_b32_e32 v43, 0xffff0000, v48
	v_pk_mul_f32 v[56:57], v[50:51], v[56:57] op_sel_hi:[0,1]
	v_lshlrev_b32_e32 v44, 16, v45
	v_and_b32_e32 v45, 0xffff0000, v45
	v_ashrrev_i32_e32 v91, 31, v90
	v_pk_fma_f32 v[56:57], v[14:15], v[56:57], v[42:43]
	v_lshlrev_b32_e32 v42, 16, v49
	v_and_b32_e32 v43, 0xffff0000, v49
	v_pk_mul_f32 v[44:45], v[50:51], v[44:45] op_sel_hi:[0,1]
	v_lshlrev_b64 v[52:53], 11, v[90:91]
	v_pk_fma_f32 v[48:49], v[16:17], v[44:45], v[42:43]
	v_pk_mul_f32 v[60:61], v[46:47], v[46:47]
	v_cvt_pk_bf16_f32 v42, v54, v55
	v_cvt_pk_bf16_f32 v43, v46, v47
	v_cvt_pk_bf16_f32 v44, v56, v57
	v_cvt_pk_bf16_f32 v45, v48, v49
	v_lshl_add_u64 v[46:47], v[82:83], 0, v[52:53]
	global_store_dwordx4 v[46:47], v[42:45], off
	v_pk_mul_f32 v[58:59], v[54:55], v[54:55]
	v_pk_mul_f32 v[62:63], v[56:57], v[56:57]
	v_lshlrev_b32_e32 v44, 16, v34
	v_and_b32_e32 v45, 0xffff0000, v34
	v_lshlrev_b32_e32 v42, 16, v38
	v_and_b32_e32 v43, 0xffff0000, v38
	v_pk_mul_f32 v[44:45], v[50:51], v[44:45] op_sel_hi:[0,1]
	v_lshlrev_b32_e32 v34, 16, v35
	v_and_b32_e32 v35, 0xffff0000, v35
	v_pk_fma_f32 v[42:43], v[2:3], v[44:45], v[42:43]
	v_lshlrev_b32_e32 v38, 16, v39
	v_and_b32_e32 v39, 0xffff0000, v39
	v_pk_mul_f32 v[34:35], v[50:51], v[34:35] op_sel_hi:[0,1]
	v_lshlrev_b32_e32 v44, 16, v36
	v_and_b32_e32 v45, 0xffff0000, v36
	v_pk_fma_f32 v[38:39], v[4:5], v[34:35], v[38:39]
	v_lshlrev_b32_e32 v34, 16, v40
	v_and_b32_e32 v35, 0xffff0000, v40
	v_pk_mul_f32 v[44:45], v[50:51], v[44:45] op_sel_hi:[0,1]
	v_lshlrev_b32_e32 v36, 16, v37
	v_and_b32_e32 v37, 0xffff0000, v37
	v_pk_fma_f32 v[44:45], v[6:7], v[44:45], v[34:35]
	v_lshlrev_b32_e32 v34, 16, v41
	v_and_b32_e32 v35, 0xffff0000, v41
	v_pk_mul_f32 v[36:37], v[50:51], v[36:37] op_sel_hi:[0,1]
	v_pk_fma_f32 v[40:41], v[8:9], v[36:37], v[34:35]
	v_pk_mul_f32 v[34:35], v[42:43], v[42:43]
	v_pk_mul_f32 v[36:37], v[38:39], v[38:39]
	v_add_f32_e32 v34, v34, v35
	v_add_f32_e32 v36, v36, v37
	v_pk_mul_f32 v[64:65], v[48:49], v[48:49]
	v_pk_mul_f32 v[48:49], v[44:45], v[44:45]
	v_add_f32_e32 v34, v34, v36
	v_add_f32_e32 v36, v60, v61
	v_add_f32_e32 v37, v58, v59
	v_pk_mul_f32 v[50:51], v[40:41], v[40:41]
	v_add_f32_e32 v35, v48, v49
	v_add_f32_e32 v36, v37, v36
	v_add_f32_e32 v37, v62, v63
	v_add_f32_e32 v50, v50, v51
	v_add_f32_e32 v34, v35, v34
	v_add_f32_e32 v35, v64, v65
	v_add_f32_e32 v36, v37, v36
	v_add_f32_e32 v34, v50, v34
	v_add_f32_e32 v35, v35, v36
	v_add_f32_e32 v48, v35, v34
	v_cvt_pk_bf16_f32 v34, v42, v43
	v_cvt_pk_bf16_f32 v35, v38, v39
	v_cvt_pk_bf16_f32 v36, v44, v45
	v_cvt_pk_bf16_f32 v37, v40, v41
	global_store_dwordx4 v[46:47], v[34:37], off offset:1024
	s_nop 1
	v_add_f32_dpp v34, v48, v48 quad_perm:[1,0,3,2] row_mask:0xf bank_mask:0xf
	s_nop 1
	v_add_f32_dpp v34, v34, v34 quad_perm:[2,3,0,1] row_mask:0xf bank_mask:0xf
	s_nop 1
	v_add_f32_dpp v34, v34, v34 row_half_mirror row_mask:0xf bank_mask:0xf
	s_nop 1
	v_add_f32_dpp v34, v34, v34 row_mirror row_mask:0xf bank_mask:0xf
	s_nop 1
	v_add_f32_dpp v34, v34, v34 row_bcast:15 row_mask:0xa bank_mask:0xf
	s_nop 1
	v_add_f32_dpp v34, v34, v34 row_bcast:31 row_mask:0xc bank_mask:0xf
	s_and_b64 exec, exec, vcc
	s_cbranch_execz .LBB0_509
	v_fmamk_f32 v34, v34, 0x3a800000, v244
	v_rsq_f32_e32 v36, v34
	v_lshl_add_u64 v[34:35], v[90:91], 2, s[14:15]
	global_store_dword v[34:35], v36, off
; __device__ __forceinline__ float bflo(unsigned w) { return __uint_as_float(w << 16); }
; __device__ __forceinline__ float bfhi(unsigned w) { return __uint_as_float(w & 0xffff0000u); }
; __device__ __forceinline__ void resid_rows(bf16_t* R, const bf16_t* Y, const float* ssqY, const float* g, float* rstd_out, float* outf, bool wf32, int row_lo, int row_hi, int yoff, int gw, int NGW, int lane) {
;     ...
;         for (int k = 0; k < RP; ++k) { const int row = row0 + k * NGW; if (row < row_hi) {
;             const float rs = __builtin_amdgcn_rsqf(ssv[k] * (1.0f / DM) + RMS_EPS); float s = 0.f;
; #pragma unroll
;             for (int j = 0; j < 2; ++j) { const int c = 8 * lane + 512 * j; const u32x4 r = rr[k][j], o = oo[k][j]; const f32x4 ga = gv[j][0], gb = gv[j][1];
;                 f32x4 ya, yb; ya[0] = bflo(r.x) + bflo(o.x) * rs * ga[0]; ya[1] = bfhi(r.x) + bfhi(o.x) * rs * ga[1]; ya[2] = bflo(r.y) + bflo(o.y) * rs * ga[2]; ya[3] = bfhi(r.y) + bfhi(o.y) * rs * ga[3];
;                 yb[0] = bflo(r.z) + bflo(o.z) * rs * gb[0]; yb[1] = bfhi(r.z) + bfhi(o.z) * rs * gb[1]; yb[2] = bflo(r.w) + bflo(o.w) * rs * gb[2]; yb[3] = bfhi(r.w) + bfhi(o.w) * rs * gb[3];
;                 if (wf32) { *(f32x4*)(outf + (size_t)row * DM + c) = ya; *(f32x4*)(outf + (size_t)row * DM + c + 4) = yb; }
;                 s += (ya[0] * ya[0] + ya[1] * ya[1]) + (ya[2] * ya[2] + ya[3] * ya[3]) + (yb[0] * yb[0] + yb[1] * yb[1]) + (yb[2] * yb[2] + yb[3] * yb[3]);
;                 u32x4 w; w.x = pk2(ya[0], ya[1]); w.y = pk2(ya[2], ya[3]); w.z = pk2(yb[0], yb[1]); w.w = pk2(yb[2], yb[3]); *(u32x4*)(R + (size_t)row * DM + c) = w; }
;             s = wave_sum(s); if (lane == 0) rstd_out[row] = __builtin_amdgcn_rsqf(s * (1.0f / DM) + RMS_EPS); } }
.LBB0_509:
	s_or_b64 exec, exec, s[8:9]
	s_and_saveexec_b64 s[6:7], s[4:5]
	s_cbranch_execz .LBB0_500
	v_fmamk_f32 v34, v89, 0x3a800000, v244
	v_rsq_f32_e32 v34, v34
	v_lshlrev_b32_e32 v40, 16, v26
	v_and_b32_e32 v41, 0xffff0000, v26
	v_lshlrev_b32_e32 v38, 16, v30
	v_and_b32_e32 v39, 0xffff0000, v30
	s_waitcnt lgkmcnt(0)
	v_pk_mul_f32 v[40:41], v[34:35], v[40:41] op_sel_hi:[0,1]
	v_lshlrev_b32_e32 v26, 16, v27
	v_and_b32_e32 v27, 0xffff0000, v27
	v_pk_fma_f32 v[38:39], v[10:11], v[40:41], v[38:39]
	v_lshlrev_b32_e32 v30, 16, v31
	v_and_b32_e32 v31, 0xffff0000, v31
	v_pk_mul_f32 v[26:27], v[34:35], v[26:27] op_sel_hi:[0,1]
	v_lshlrev_b32_e32 v40, 16, v28
	v_and_b32_e32 v41, 0xffff0000, v28
	v_pk_fma_f32 v[30:31], v[12:13], v[26:27], v[30:31]
	v_lshlrev_b32_e32 v26, 16, v32
	v_and_b32_e32 v27, 0xffff0000, v32
	v_pk_mul_f32 v[40:41], v[34:35], v[40:41] op_sel_hi:[0,1]
	v_lshlrev_b32_e32 v28, 16, v29
	v_and_b32_e32 v29, 0xffff0000, v29
	v_ashrrev_i32_e32 v89, 31, v88
	v_pk_fma_f32 v[40:41], v[14:15], v[40:41], v[26:27]
	v_lshlrev_b32_e32 v26, 16, v33
	v_and_b32_e32 v27, 0xffff0000, v33
	v_pk_mul_f32 v[28:29], v[34:35], v[28:29] op_sel_hi:[0,1]
	v_lshlrev_b64 v[36:37], 11, v[88:89]
	v_pk_fma_f32 v[32:33], v[16:17], v[28:29], v[26:27]
	v_pk_mul_f32 v[44:45], v[30:31], v[30:31]
	v_cvt_pk_bf16_f32 v26, v38, v39
	v_cvt_pk_bf16_f32 v27, v30, v31
	v_cvt_pk_bf16_f32 v28, v40, v41
	v_cvt_pk_bf16_f32 v29, v32, v33
	v_lshl_add_u64 v[30:31], v[82:83], 0, v[36:37]
	global_store_dwordx4 v[30:31], v[26:29], off
	v_pk_mul_f32 v[42:43], v[38:39], v[38:39]
	v_pk_mul_f32 v[46:47], v[40:41], v[40:41]
	v_lshlrev_b32_e32 v28, 16, v18
	v_and_b32_e32 v29, 0xffff0000, v18
	v_lshlrev_b32_e32 v26, 16, v22
	v_and_b32_e32 v27, 0xffff0000, v22
	v_pk_mul_f32 v[28:29], v[34:35], v[28:29] op_sel_hi:[0,1]
	v_lshlrev_b32_e32 v18, 16, v19
	v_and_b32_e32 v19, 0xffff0000, v19
	v_pk_fma_f32 v[26:27], v[2:3], v[28:29], v[26:27]
	v_lshlrev_b32_e32 v22, 16, v23
	v_and_b32_e32 v23, 0xffff0000, v23
	v_pk_mul_f32 v[18:19], v[34:35], v[18:19] op_sel_hi:[0,1]
	v_lshlrev_b32_e32 v28, 16, v20
	v_and_b32_e32 v29, 0xffff0000, v20
	v_pk_fma_f32 v[22:23], v[4:5], v[18:19], v[22:23]
	v_lshlrev_b32_e32 v18, 16, v24
	v_and_b32_e32 v19, 0xffff0000, v24
	v_pk_mul_f32 v[28:29], v[34:35], v[28:29] op_sel_hi:[0,1]
	v_lshlrev_b32_e32 v20, 16, v21
	v_and_b32_e32 v21, 0xffff0000, v21
	v_pk_fma_f32 v[28:29], v[6:7], v[28:29], v[18:19]
	v_lshlrev_b32_e32 v18, 16, v25
	v_and_b32_e32 v19, 0xffff0000, v25
	v_pk_mul_f32 v[20:21], v[34:35], v[20:21] op_sel_hi:[0,1]
	v_pk_fma_f32 v[24:25], v[8:9], v[20:21], v[18:19]
	v_pk_mul_f32 v[18:19], v[26:27], v[26:27]
	v_pk_mul_f32 v[20:21], v[22:23], v[22:23]
	v_add_f32_e32 v18, v18, v19
	v_add_f32_e32 v20, v20, v21
	v_pk_mul_f32 v[48:49], v[32:33], v[32:33]
	v_pk_mul_f32 v[32:33], v[28:29], v[28:29]
	v_add_f32_e32 v18, v18, v20
	v_add_f32_e32 v20, v44, v45
	v_add_f32_e32 v21, v42, v43
	v_pk_mul_f32 v[34:35], v[24:25], v[24:25]
	v_add_f32_e32 v19, v32, v33
	v_add_f32_e32 v20, v21, v20
	v_add_f32_e32 v21, v46, v47
	v_add_f32_e32 v34, v34, v35
	v_add_f32_e32 v18, v19, v18
	v_add_f32_e32 v19, v48, v49
	v_add_f32_e32 v20, v21, v20
	v_add_f32_e32 v18, v34, v18
	v_add_f32_e32 v19, v19, v20
	v_add_f32_e32 v32, v19, v18
	v_cvt_pk_bf16_f32 v18, v26, v27
	v_cvt_pk_bf16_f32 v19, v22, v23
	v_cvt_pk_bf16_f32 v20, v28, v29
	v_cvt_pk_bf16_f32 v21, v24, v25
	global_store_dwordx4 v[30:31], v[18:21], off offset:1024
	s_nop 1
	v_add_f32_dpp v18, v32, v32 quad_perm:[1,0,3,2] row_mask:0xf bank_mask:0xf
	s_nop 1
	v_add_f32_dpp v18, v18, v18 quad_perm:[2,3,0,1] row_mask:0xf bank_mask:0xf
	s_nop 1
	v_add_f32_dpp v18, v18, v18 row_half_mirror row_mask:0xf bank_mask:0xf
	s_nop 1
	v_add_f32_dpp v18, v18, v18 row_mirror row_mask:0xf bank_mask:0xf
	s_nop 1
	v_add_f32_dpp v18, v18, v18 row_bcast:15 row_mask:0xa bank_mask:0xf
	s_nop 1
	v_add_f32_dpp v18, v18, v18 row_bcast:31 row_mask:0xc bank_mask:0xf
	s_and_b64 exec, exec, vcc
	s_cbranch_execz .LBB0_500
	v_fmamk_f32 v18, v18, 0x3a800000, v244
	v_rsq_f32_e32 v20, v18
	v_lshl_add_u64 v[18:19], v[88:89], 2, s[14:15]
	global_store_dword v[18:19], v20, off
	s_branch .LBB0_500
